# attention: first three K fragment pairs requested right after the loop-top barrier, ahead of the LDS-DMA issue block
# baseline (speedup 1.0000x reference)
.LBB0_845:
	s_waitcnt vmcnt(0)
	s_waitcnt lgkmcnt(0)
	s_add_i32 s0, s33, -1
	s_and_b32 s50, s0, 1
	v_cmp_lt_u32_e32 vcc, s33, v137
	s_barrier
	s_lshl_b32 s58, s50, 15
	v_add_u32_e32 v173, s58, v152
	v_add_u32_e32 v80, v173, v156
	v_add_u32_e32 v182, v173, v157
	v_add_u32_e32 v186, v173, v158
	ds_read_b128 v[174:177], v80
	ds_read_b128 v[178:181], v80 offset:8192
	ds_read_b128 v[208:211], v182
	ds_read_b128 v[182:185], v182 offset:8192
	ds_read_b128 v[212:215], v186
	ds_read_b128 v[186:189], v186 offset:8192
	s_and_saveexec_b64 s[0:1], vcc
	s_cbranch_execz .LBB0_847
	s_lshl_b32 s48, s50, 15
	s_xor_b32 s48, s48, 0x8000
	s_add_u32 s48, s48, s60
	s_mov_b32 m0, s48
	s_nop 0
	global_load_lds_dwordx4 v200, s[98:99]
	s_add_u32 m0, s48, 0x4000
	s_nop 0
	global_load_lds_dwordx4 v204, s[100:101]
	s_add_u32 m0, s48, 0x1000
	s_nop 0
	global_load_lds_dwordx4 v201, s[98:99]
	s_add_u32 m0, s48, 0x5000
	s_nop 0
	global_load_lds_dwordx4 v205, s[100:101]
	s_add_u32 m0, s48, 0x2000
	s_nop 0
	global_load_lds_dwordx4 v202, s[98:99]
	s_add_u32 m0, s48, 0x6000
	s_nop 0
	global_load_lds_dwordx4 v206, s[100:101]
	s_add_u32 m0, s48, 0x3000
	s_nop 0
	global_load_lds_dwordx4 v203, s[98:99]
	s_add_u32 m0, s48, 0x7000
	s_add_u32 s98, s98, s28
	global_load_lds_dwordx4 v207, s[100:101]
	s_addc_u32 s99, s99, s29
	s_add_u32 s100, s100, s40
	s_addc_u32 s101, s101, s41
.LBB0_847:
	s_or_b64 exec, exec, s[0:1]
	v_add_u32_e32 v133, 64, v172
	s_and_saveexec_b64 s[0:1], s[10:11]
	s_xor_b64 s[0:1], exec, s[0:1]
	v_add_u32_e32 v133, 64, v172
	s_andn2_saveexec_b64 s[48:49], s[0:1]
	s_cbranch_execz .LBB0_844
	s_lshl_b32 s0, s50, 15
	s_add_i32 s58, s0, 0
	v_add_u32_e32 v173, v173, v159
	v_cmp_gt_u32_e32 vcc, v133, v171
	s_waitcnt lgkmcnt(4)
	v_mfma_f32_32x32x16_bf16 v[80:95], v[174:177], v[96:99], v[232:247]
	v_mfma_f32_32x32x16_bf16 v[64:79], v[178:181], v[96:99], v[232:247]
	ds_read_b128 v[174:177], v173
	ds_read_b128 v[190:193], v173 offset:8192
	s_waitcnt lgkmcnt(4)
	v_mfma_f32_32x32x16_bf16 v[80:95], v[208:211], v[100:103], v[80:95]
	v_mfma_f32_32x32x16_bf16 v[64:79], v[182:185], v[100:103], v[64:79]
	s_waitcnt lgkmcnt(2)
	v_mfma_f32_32x32x16_bf16 v[80:95], v[212:215], v[104:107], v[80:95]
	v_mfma_f32_32x32x16_bf16 v[64:79], v[186:189], v[104:107], v[64:79]
	s_waitcnt lgkmcnt(0)
	v_mfma_f32_32x32x16_bf16 v[80:95], v[174:177], v[108:111], v[80:95]
	v_mfma_f32_32x32x16_bf16 v[64:79], v[190:193], v[108:111], v[64:79]
	s_and_saveexec_b64 s[50:51], vcc
	s_cbranch_execz .LBB0_852
	v_add_u32_e32 v172, v114, v172
	v_add_u32_e32 v173, 1, v172
	v_cmp_lt_u32_e32 vcc, v172, v171
	v_cmp_lt_u32_e64 s[0:1], v173, v171
	s_or_b64 vcc, s[0:1], vcc
	v_add_u32_e32 v173, 2, v172
	s_nop 2
	v_cndmask_b32_e32 v80, v169, v80, vcc
	v_cmp_lt_u32_e32 vcc, v173, v171
	v_add_u32_e32 v173, 3, v172
	v_cndmask_b32_e64 v81, v169, v81, s[0:1]
	v_cndmask_b32_e32 v82, v169, v82, vcc
	v_cmp_lt_u32_e32 vcc, v173, v171
	v_add_u32_e32 v173, 4, v172
	s_nop 0
	v_cndmask_b32_e32 v83, v169, v83, vcc
	v_cmp_lt_u32_e32 vcc, v173, v171
	v_add_u32_e32 v173, 5, v172
	s_nop 0
	v_cndmask_b32_e32 v84, v169, v84, vcc
	v_cmp_lt_u32_e32 vcc, v173, v171
	v_add_u32_e32 v173, 6, v172
	s_nop 0
	v_cndmask_b32_e32 v85, v169, v85, vcc
	v_cmp_lt_u32_e32 vcc, v173, v171
	v_add_u32_e32 v173, 7, v172
	s_nop 0
	v_cndmask_b32_e32 v86, v169, v86, vcc
	v_cmp_lt_u32_e32 vcc, v173, v171
	v_add_u32_e32 v173, 16, v172
	s_nop 0
	v_cndmask_b32_e32 v87, v169, v87, vcc
	v_cmp_lt_u32_e32 vcc, v173, v171
	v_add_u32_e32 v173, 17, v172
	s_nop 0
	v_cndmask_b32_e32 v88, v169, v88, vcc
	v_cmp_lt_u32_e32 vcc, v173, v171
	v_add_u32_e32 v173, 18, v172
	s_nop 0
	v_cndmask_b32_e32 v89, v169, v89, vcc
	v_cmp_lt_u32_e32 vcc, v173, v171
	v_add_u32_e32 v173, 19, v172
	s_nop 0
	v_cndmask_b32_e32 v90, v169, v90, vcc
	v_cmp_lt_u32_e32 vcc, v173, v171
	v_add_u32_e32 v173, 20, v172
	s_nop 0
	v_cndmask_b32_e32 v91, v169, v91, vcc
	v_cmp_lt_u32_e32 vcc, v173, v171
	v_add_u32_e32 v173, 21, v172
	s_nop 0
	v_cndmask_b32_e32 v92, v169, v92, vcc
	v_cmp_lt_u32_e32 vcc, v173, v171
	v_add_u32_e32 v173, 22, v172
	s_nop 0
	v_cndmask_b32_e32 v93, v169, v93, vcc
	v_cmp_lt_u32_e32 vcc, v173, v171
	v_add_u32_e32 v173, 23, v172
	s_nop 0
	v_cndmask_b32_e32 v94, v169, v94, vcc
	v_cmp_lt_u32_e32 vcc, v173, v171
	v_add_u32_e32 v173, 32, v172
	v_cmp_lt_u32_e64 s[0:1], v173, v171
	s_or_b64 vcc, s[0:1], vcc
	v_add_u32_e32 v173, 33, v172
	v_cndmask_b32_e32 v95, v169, v95, vcc
	v_cmp_lt_u32_e32 vcc, v173, v171
	v_add_u32_e32 v173, 34, v172
	v_cndmask_b32_e64 v64, v169, v64, s[0:1]
	v_cndmask_b32_e32 v65, v169, v65, vcc
	v_cmp_lt_u32_e32 vcc, v173, v171
	v_add_u32_e32 v173, 35, v172
	s_nop 0
	v_cndmask_b32_e32 v66, v169, v66, vcc
	v_cmp_lt_u32_e32 vcc, v173, v171
	v_add_u32_e32 v173, 36, v172
	s_nop 0
	v_cndmask_b32_e32 v67, v169, v67, vcc
	v_cmp_lt_u32_e32 vcc, v173, v171
	v_add_u32_e32 v173, 37, v172
	s_nop 0
	v_cndmask_b32_e32 v68, v169, v68, vcc
	v_cmp_lt_u32_e32 vcc, v173, v171
	v_add_u32_e32 v173, 38, v172
	s_nop 0
	v_cndmask_b32_e32 v69, v169, v69, vcc
	v_cmp_lt_u32_e32 vcc, v173, v171
	v_add_u32_e32 v173, 39, v172
	s_nop 0
	v_cndmask_b32_e32 v70, v169, v70, vcc
	v_cmp_lt_u32_e32 vcc, v173, v171
	v_add_u32_e32 v173, 48, v172
	s_nop 0
	v_cndmask_b32_e32 v71, v169, v71, vcc
	v_cmp_lt_u32_e32 vcc, v173, v171
	v_add_u32_e32 v173, 49, v172
	s_nop 0
	v_cndmask_b32_e32 v72, v169, v72, vcc
	v_cmp_lt_u32_e32 vcc, v173, v171
	v_add_u32_e32 v173, 50, v172
	s_nop 0
	v_cndmask_b32_e32 v73, v169, v73, vcc
	v_cmp_lt_u32_e32 vcc, v173, v171
	v_add_u32_e32 v173, 51, v172
	s_nop 0
	v_cndmask_b32_e32 v74, v169, v74, vcc
	v_cmp_lt_u32_e32 vcc, v173, v171
	v_add_u32_e32 v173, 52, v172
	s_nop 0
	v_cndmask_b32_e32 v75, v169, v75, vcc
	v_cmp_lt_u32_e32 vcc, v173, v171
	v_add_u32_e32 v173, 53, v172
	s_nop 0
	v_cndmask_b32_e32 v76, v169, v76, vcc
	v_cmp_lt_u32_e32 vcc, v173, v171
	v_add_u32_e32 v173, 54, v172
	v_add_u32_e32 v172, 55, v172
	v_cndmask_b32_e32 v77, v169, v77, vcc
	v_cmp_lt_u32_e32 vcc, v173, v171
	s_nop 1
	v_cndmask_b32_e32 v78, v169, v78, vcc
	v_cmp_lt_u32_e32 vcc, v172, v171
	s_nop 1
	v_cndmask_b32_e32 v79, v169, v79, vcc
